# v21
# baseline (speedup 1.0000x reference)
; DI void dsa_item(const Params& p, int b, int blk) {
;     ...
;     for (int slot = tid; slot < 2048; slot += NTHREADS) {
;       int f = slot >> 6, ln = slot & 63, hd = f >> 2, s = f & 3;
;       *(u32x4*)(smem + DS_FRAGQ + slot * 16) =
;           ldg<u32x4>(Iq + (rowbase + q0 + (ln & 31)) * 512 + hd * 64 + 16 * s + 8 * (ln >> 5));
;     }
.LBB0_937:
	v_ashrrev_i32_e32 v0, 2, v5
	v_and_b32_e32 v6, 0xffffffc0, v0
	v_lshrrev_b32_e32 v8, 1, v5
	v_ashrrev_i32_e32 v7, 31, v6
	v_and_b32_e32 v0, 0x60, v8
	v_lshl_add_u64 v[6:7], v[6:7], 1, v[2:3]
	v_lshl_add_u64 v[6:7], v[6:7], 0, v[0:1]
	v_and_b32_e32 v0, 16, v8
	v_lshl_add_u64 v[22:23], v[6:7], 0, v[0:1]
	global_load_dwordx4 v[6:9], v[22:23], off
	global_load_dwordx4 v[10:13], v[22:23], off offset:256
	global_load_dwordx4 v[14:17], v[22:23], off offset:512
	global_load_dwordx4 v[18:21], v[22:23], off offset:768
	s_waitcnt vmcnt(3)
	ds_write_b128 v4, v[6:9]
	s_waitcnt vmcnt(2)
	ds_write_b128 v4, v[10:13] offset:8192
	s_waitcnt vmcnt(1)
	ds_write_b128 v4, v[14:17] offset:16384
	s_waitcnt vmcnt(0)
	ds_write_b128 v4, v[18:21] offset:24576
; DI unsigned pack2(float a, float b) { fl2_t v = {a, b}; bf2_t r = __builtin_convertvector(v, bf2_t); return __builtin_bit_cast(unsigned, r); }
; DI float bflo(unsigned u) { return __uint_as_float(u << 16); }
; DI float bfhi(unsigned u) { return __uint_as_float(u & 0xffff0000u); }
; DI void dsa_item(const Params& p, int b, int blk) {
;     ...
;     if (tid < 256) {
;       const int s = tid >> 6, ln = tid & 63, qr = ln & 31, hq = ln >> 5;
;       float accq[8] = {0, 0, 0, 0, 0, 0, 0, 0};
;       for (int hd = 0; hd < 8; ++hd) {
;         const float wq = Iw[(rowbase + q0 + qr) * 8 + hd] * 0.04419417382415922f;
;         u32x4 v = ldg<u32x4>(Iq + (rowbase + q0 + qr) * 512 + hd * 64 + 16 * s + 8 * hq);
;         accq[0] += wq * bflo(v[0]); accq[1] += wq * bfhi(v[0]); accq[2] += wq * bflo(v[1]); accq[3] += wq * bfhi(v[1]);
;         accq[4] += wq * bflo(v[2]); accq[5] += wq * bfhi(v[2]); accq[6] += wq * bflo(v[3]); accq[7] += wq * bfhi(v[3]);
;       }
;       u32x4 o; o[0] = pack2(accq[0], accq[1]); o[1] = pack2(accq[2], accq[3]); o[2] = pack2(accq[4], accq[5]); o[3] = pack2(accq[6], accq[7]);
;       *(u32x4*)(smem + DS_QBAR + tid * 16) = o;
;     }
.LBB0_938:
	s_or_b64 exec, exec, s[0:1]
	v_lshrrev_b32_e32 v31, 5, v187
	s_add_u32 s0, s14, 0x167dda00
	s_addc_u32 s1, s15, 0
	v_cmp_gt_i32_e32 vcc, s23, v189
	v_lshlrev_b32_e32 v0, 4, v31
	s_and_saveexec_b64 s[4:5], vcc
	s_cbranch_execz .LBB0_940
	s_add_u32 s10, s16, s36
	s_addc_u32 s11, s17, 0
	s_waitcnt vmcnt(0)
	v_or_b32_e32 v2, s10, v202
	v_mov_b32_e32 v3, s11
	v_lshlrev_b64 v[4:5], 5, v[2:3]
	v_lshl_add_u64 v[14:15], s[0:1], 0, v[4:5]
	v_lshlrev_b64 v[2:3], 10, v[2:3]
	v_lshlrev_b32_e32 v4, 4, v188
	v_lshl_add_u64 v[2:3], s[8:9], 0, v[2:3]
	v_ashrrev_i32_e32 v5, 31, v4
	v_lshl_add_u64 v[2:3], v[4:5], 1, v[2:3]
	v_lshl_add_u64 v[28:29], v[2:3], 0, v[0:1]
	flat_load_dwordx4 v[2:5], v[14:15]
	global_load_dwordx4 v[6:9], v[28:29], off
	global_load_dwordx4 v[10:13], v[28:29], off offset:128
	global_load_dwordx4 v[60:63], v[28:29], off offset:256
	global_load_dwordx4 v[64:67], v[28:29], off offset:384
	flat_load_dwordx4 v[68:71], v[14:15] offset:16
	global_load_dwordx4 v[72:75], v[28:29], off offset:640
	global_load_dwordx4 v[76:79], v[28:29], off offset:512
	global_load_dwordx4 v[80:83], v[28:29], off offset:768
	global_load_dwordx4 v[84:87], v[28:29], off offset:896
	s_waitcnt vmcnt(0) lgkmcnt(0)
	v_mul_f32_e32 v32, 0x3d3504f3, v2
	v_lshlrev_b32_e32 v52, 16, v6
	v_and_b32_e32 v53, 0xffff0000, v6
	v_lshlrev_b32_e32 v50, 16, v7
	v_and_b32_e32 v51, 0xffff0000, v7
	v_lshlrev_b32_e32 v48, 16, v8
	v_and_b32_e32 v49, 0xffff0000, v8
	v_lshlrev_b32_e32 v38, 16, v9
	v_and_b32_e32 v39, 0xffff0000, v9
	v_mul_f32_e32 v36, 0x3d3504f3, v3
	v_mul_f32_e32 v34, 0x3d3504f3, v4
	v_mov_b64_e32 v[6:7], v[60:61]
	v_mov_b64_e32 v[8:9], v[62:63]
	v_mul_f32_e32 v30, 0x3d3504f3, v5
	v_mov_b64_e32 v[2:3], v[64:65]
	v_mov_b64_e32 v[4:5], v[66:67]
	v_mov_b64_e32 v[24:25], v[68:69]
	v_mov_b64_e32 v[26:27], v[70:71]
	v_mov_b64_e32 v[18:19], v[72:73]
	v_mov_b64_e32 v[20:21], v[74:75]
	v_pk_fma_f32 v[52:53], v[32:33], v[52:53], 0 op_sel_hi:[0,1,0]
	v_mov_b64_e32 v[14:15], v[76:77]
	v_mov_b64_e32 v[16:17], v[78:79]
	v_lshlrev_b32_e32 v54, 16, v10
	v_and_b32_e32 v55, 0xffff0000, v10
	v_pk_fma_f32 v[50:51], v[32:33], v[50:51], 0 op_sel_hi:[0,1,0]
	v_lshlrev_b32_e32 v10, 16, v11
	v_and_b32_e32 v11, 0xffff0000, v11
	v_pk_fma_f32 v[52:53], v[36:37], v[54:55], v[52:53] op_sel_hi:[0,1,1]
	v_pk_fma_f32 v[10:11], v[36:37], v[10:11], v[50:51] op_sel_hi:[0,1,1]
	s_waitcnt vmcnt(0)
	v_lshlrev_b32_e32 v54, 16, v6
	v_and_b32_e32 v55, 0xffff0000, v6
	s_waitcnt lgkmcnt(0)
	v_mul_f32_e32 v40, 0x3d3504f3, v24
	v_mul_f32_e32 v42, 0x3d3504f3, v25
	v_mov_b64_e32 v[22:23], v[80:81]
	v_mov_b64_e32 v[24:25], v[82:83]
	v_mul_f32_e32 v44, 0x3d3504f3, v26
	v_mul_f32_e32 v46, 0x3d3504f3, v27
	v_mov_b64_e32 v[26:27], v[84:85]
	v_mov_b64_e32 v[28:29], v[86:87]
	v_lshlrev_b32_e32 v6, 16, v7
	v_and_b32_e32 v7, 0xffff0000, v7
	v_pk_fma_f32 v[52:53], v[34:35], v[54:55], v[52:53] op_sel_hi:[0,1,1]
	v_lshlrev_b32_e32 v54, 16, v2
	v_and_b32_e32 v55, 0xffff0000, v2
	v_pk_fma_f32 v[6:7], v[34:35], v[6:7], v[10:11] op_sel_hi:[0,1,1]
	v_lshlrev_b32_e32 v2, 16, v3
	v_and_b32_e32 v3, 0xffff0000, v3
	v_pk_fma_f32 v[2:3], v[30:31], v[2:3], v[6:7] op_sel_hi:[0,1,1]
	v_lshlrev_b32_e32 v6, 16, v15
	v_and_b32_e32 v7, 0xffff0000, v15
	v_pk_fma_f32 v[2:3], v[40:41], v[6:7], v[2:3] op_sel_hi:[0,1,1]
	v_lshlrev_b32_e32 v6, 16, v19
	v_and_b32_e32 v7, 0xffff0000, v19
	v_pk_fma_f32 v[2:3], v[42:43], v[6:7], v[2:3] op_sel_hi:[0,1,1]
	v_lshlrev_b32_e32 v10, 16, v12
	v_and_b32_e32 v11, 0xffff0000, v12
	v_lshlrev_b32_e32 v12, 16, v13
	v_and_b32_e32 v13, 0xffff0000, v13
	v_pk_fma_f32 v[52:53], v[30:31], v[54:55], v[52:53] op_sel_hi:[0,1,1]
	v_lshlrev_b32_e32 v54, 16, v14
	v_and_b32_e32 v55, 0xffff0000, v14
	v_pk_fma_f32 v[52:53], v[40:41], v[54:55], v[52:53] op_sel_hi:[0,1,1]
	v_lshlrev_b32_e32 v54, 16, v18
	v_and_b32_e32 v55, 0xffff0000, v18
	v_pk_fma_f32 v[52:53], v[42:43], v[54:55], v[52:53] op_sel_hi:[0,1,1]
	s_waitcnt vmcnt(1)
	v_lshlrev_b32_e32 v6, 16, v23
	v_and_b32_e32 v7, 0xffff0000, v23
	v_pk_fma_f32 v[2:3], v[44:45], v[6:7], v[2:3] op_sel_hi:[0,1,1]
	s_waitcnt vmcnt(0)
	v_lshlrev_b32_e32 v6, 16, v27
	v_and_b32_e32 v7, 0xffff0000, v27
	v_pk_fma_f32 v[6:7], v[46:47], v[6:7], v[2:3] op_sel_hi:[0,1,1]
	v_pk_fma_f32 v[2:3], v[32:33], v[48:49], 0 op_sel_hi:[0,1,0]
	v_pk_fma_f32 v[2:3], v[36:37], v[10:11], v[2:3] op_sel_hi:[0,1,1]
	v_lshlrev_b32_e32 v10, 16, v8
	v_and_b32_e32 v11, 0xffff0000, v8
	v_pk_fma_f32 v[2:3], v[34:35], v[10:11], v[2:3] op_sel_hi:[0,1,1]
	v_lshlrev_b32_e32 v10, 16, v4
	v_and_b32_e32 v11, 0xffff0000, v4
	v_pk_fma_f32 v[2:3], v[30:31], v[10:11], v[2:3] op_sel_hi:[0,1,1]
	v_lshlrev_b32_e32 v10, 16, v16
	v_and_b32_e32 v11, 0xffff0000, v16
	v_pk_fma_f32 v[2:3], v[40:41], v[10:11], v[2:3] op_sel_hi:[0,1,1]
	v_lshlrev_b32_e32 v10, 16, v20
	v_and_b32_e32 v11, 0xffff0000, v20
	v_pk_fma_f32 v[2:3], v[42:43], v[10:11], v[2:3] op_sel_hi:[0,1,1]
	v_lshlrev_b32_e32 v10, 16, v24
	v_and_b32_e32 v11, 0xffff0000, v24
	v_pk_fma_f32 v[2:3], v[44:45], v[10:11], v[2:3] op_sel_hi:[0,1,1]
	v_lshlrev_b32_e32 v10, 16, v28
	v_and_b32_e32 v11, 0xffff0000, v28
	v_pk_fma_f32 v[10:11], v[46:47], v[10:11], v[2:3] op_sel_hi:[0,1,1]
	v_pk_fma_f32 v[2:3], v[32:33], v[38:39], 0 op_sel_hi:[0,1,0]
	v_pk_fma_f32 v[2:3], v[36:37], v[12:13], v[2:3] op_sel_hi:[0,1,1]
	v_lshlrev_b32_e32 v8, 16, v9
	v_and_b32_e32 v9, 0xffff0000, v9
	v_pk_fma_f32 v[2:3], v[34:35], v[8:9], v[2:3] op_sel_hi:[0,1,1]
	v_lshlrev_b32_e32 v4, 16, v5
	v_and_b32_e32 v5, 0xffff0000, v5
	v_pk_fma_f32 v[2:3], v[30:31], v[4:5], v[2:3] op_sel_hi:[0,1,1]
	v_lshlrev_b32_e32 v4, 16, v17
	v_and_b32_e32 v5, 0xffff0000, v17
	v_pk_fma_f32 v[2:3], v[40:41], v[4:5], v[2:3] op_sel_hi:[0,1,1]
	v_lshlrev_b32_e32 v4, 16, v21
	v_and_b32_e32 v5, 0xffff0000, v21
	v_lshlrev_b32_e32 v54, 16, v22
	v_and_b32_e32 v55, 0xffff0000, v22
	v_pk_fma_f32 v[2:3], v[42:43], v[4:5], v[2:3] op_sel_hi:[0,1,1]
	v_lshlrev_b32_e32 v4, 16, v25
	v_and_b32_e32 v5, 0xffff0000, v25
	v_pk_fma_f32 v[52:53], v[44:45], v[54:55], v[52:53] op_sel_hi:[0,1,1]
	v_lshlrev_b32_e32 v54, 16, v26
	v_and_b32_e32 v55, 0xffff0000, v26
	v_pk_fma_f32 v[2:3], v[44:45], v[4:5], v[2:3] op_sel_hi:[0,1,1]
	v_lshlrev_b32_e32 v4, 16, v29
	v_and_b32_e32 v5, 0xffff0000, v29
	v_pk_fma_f32 v[52:53], v[46:47], v[54:55], v[52:53] op_sel_hi:[0,1,1]
	v_pk_fma_f32 v[8:9], v[46:47], v[4:5], v[2:3] op_sel_hi:[0,1,1]
	v_cvt_pk_bf16_f32 v3, v6, v7
	v_lshl_add_u32 v6, v189, 4, 0
	v_cvt_pk_bf16_f32 v2, v52, v53
	v_cvt_pk_bf16_f32 v4, v10, v11
	v_cvt_pk_bf16_f32 v5, v8, v9
	v_add_u32_e32 v6, 0x24e00, v6
	ds_write_b128 v6, v[2:5]

; DI int crow(int reg, int h) { return (reg & 3) + 8 * (reg >> 2) + 4 * h; }
; #define MFMA32(a, b, c) __builtin_amdgcn_mfma_f32_32x32x16_bf16((a), (b), (c), 0, 0, 0)
;     ...
;       const bf16x8* fb = (const bf16x8*)(smem + DS_QBAR);
;       #pragma unroll
;       for (int s = 0; s < 4; ++s) sc = MFMA32(a[s], fb[s * 64 + lane], sc);
;       for (int i = 0; i < 16; ++i) sc[i] *= 0.5f;
;     }
;     #pragma unroll
;     for (int hd = 0; hd < 8; ++hd) {
;       f32x16 acc;
;       for (int i = 0; i < 16; ++i) acc[i] = 0.f;
;       #pragma unroll
;       for (int s = 0; s < 4; ++s) acc = MFMA32(a[s], fq[(hd * 4 + s) * 64 + lane], acc);
;       for (int i = 0; i < 16; ++i) sc[i] = fmaf(wv[hd], __builtin_fabsf(acc[i]), sc[i]);
; DI void dsa_item(const Params& p, int b, int blk) {
;     ...
;     float wv[8];
;     for (int hd = 0; hd < 8; ++hd) wv[hd] = Iw[(rowbase + q0 + r) * 8 + hd] * (0.5f * 0.04419417382415922f);
;     const u16* Ikb = Ik + rowbase * 64;
;     const int nt = blk + 1;
;     const int qpos = q0 + r;
;     __syncthreads();
;     float* ssum = (float*)(smem + DS_SAMP); float* ssq = ssum + 32; float* scnt = ssq + 32; unsigned* oflow = (unsigned*)(scnt + 32);
;     {
;       const int kt_s = min(nt - 1, (w * nt) >> 3);
;       score_pass(Ikb, wv, kt_s + 1, kt_s, lane, [&](const f32x16& sc, int kt) {
;         float s1 = 0.f, s2 = 0.f, c = 0.f;
;         for (int i = 0; i < 16; ++i) { int key = kt * 32 + crow(i, hh); if (key <= qpos) { s1 += sc[i]; s2 += sc[i] * sc[i]; c += 1.f; } }
;         atomicAdd(&ssum[r], s1); atomicAdd(&ssq[r], s2); atomicAdd(&scnt[r], c);
;       });
;     }
.LBB0_950:
	s_or_b64 exec, exec, s[4:5]
	s_add_u32 s4, s16, s36
	s_addc_u32 s5, s17, 0
	s_waitcnt vmcnt(0)
	v_or_b32_e32 v2, s4, v202
	v_mov_b32_e32 v3, s5
	v_lshlrev_b64 v[2:3], 5, v[2:3]
	v_lshl_add_u64 v[6:7], s[0:1], 0, v[2:3]
	flat_load_dwordx4 v[2:5], v[6:7]
	flat_load_dwordx4 v[60:63], v[6:7] offset:16
	s_mul_hi_u32 s0, s19, 0x104000
	s_mul_i32 s19, s19, 0x104000
	s_add_u32 s1, s14, s19
	s_addc_u32 s0, s15, s0
	s_add_u32 s4, s1, 0x163cda00
	s_addc_u32 s5, s0, 0
	s_sub_i32 s0, 0x101, s18
	v_lshlrev_b32_e32 v34, 3, v31
	v_lshlrev_b32_e32 v201, 2, v31
	v_lshl_add_u32 v199, v187, 4, 0
	v_add_u32_e32 v200, 0x24e00, v199
	v_or_b32_e32 v198, s36, v202
	v_lshl_add_u32 v205, v202, 2, 0
	v_add_u32_e32 v36, 0x25f00, v205
	v_add_u32_e32 v37, 0x25e00, v205
	v_add_u32_e32 v35, 0x25e80, v205
	v_cmp_ge_i32_e64 s[8:9], s37, v188
	s_waitcnt vmcnt(0)
	v_mov_b32_e32 v130, 0
	v_mov_b32_e32 v131, 0
	v_mov_b32_e32 v132, 0
	v_mov_b32_e32 v133, 0
	v_mov_b32_e32 v162, 0
	v_mov_b32_e32 v163, 0
	v_mov_b32_e32 v164, 0
	v_mov_b32_e32 v165, 0
	v_mov_b32_e32 v166, 0
	v_mov_b32_e32 v167, 0
	v_mov_b32_e32 v168, 0
	v_mov_b32_e32 v169, 0
	v_mov_b32_e32 v170, 0
	v_mov_b32_e32 v171, 0
	v_mov_b32_e32 v172, 0
	v_mov_b32_e32 v173, 0
	s_waitcnt lgkmcnt(0)
	v_mul_f32_e32 v190, 0x3cb504f3, v2
	v_mul_f32_e32 v191, 0x3cb504f3, v3
	v_mul_f32_e32 v192, 0x3cb504f3, v4
	v_mul_f32_e32 v193, 0x3cb504f3, v5
	v_mov_b64_e32 v[2:3], v[60:61]
	v_mov_b64_e32 v[4:5], v[62:63]
	v_mul_f32_e32 v194, 0x3cb504f3, v2
	v_mul_f32_e32 v195, 0x3cb504f3, v3
	v_mul_f32_e32 v196, 0x3cb504f3, v4
	v_mul_f32_e32 v197, 0x3cb504f3, v5
	v_mul_lo_u32 v2, v188, s0
	v_ashrrev_i32_e32 v2, 3, v2
	v_min_i32_e32 v2, s37, v2
	v_lshlrev_b32_e32 v38, 5, v2
	v_or_b32_e32 v2, v38, v202
	v_ashrrev_i32_e32 v3, 31, v2
	v_lshlrev_b64 v[2:3], 7, v[2:3]
	v_lshl_add_u64 v[2:3], s[4:5], 0, v[2:3]
	v_lshl_add_u64 v[2:3], v[2:3], 0, v[0:1]
	global_load_dwordx4 v[30:33], v[2:3], off
	global_load_dwordx4 v[26:29], v[2:3], off offset:32
	global_load_dwordx4 v[22:25], v[2:3], off offset:64
	global_load_dwordx4 v[18:21], v[2:3], off offset:96
	s_waitcnt lgkmcnt(0)
	s_barrier
	ds_read_b128 v[2:5], v200
	ds_read_b128 v[40:43], v200 offset:1024
	s_waitcnt vmcnt(3) lgkmcnt(1)
	v_mfma_f32_32x32x16_bf16 v[2:17], v[30:33], v[2:5], 0
	s_waitcnt vmcnt(2) lgkmcnt(0)
	v_mfma_f32_32x32x16_bf16 v[2:17], v[26:29], v[40:43], v[2:17]
	ds_read_b128 v[40:43], v200 offset:2048
	s_waitcnt vmcnt(1) lgkmcnt(0)
	v_mfma_f32_32x32x16_bf16 v[2:17], v[22:25], v[40:43], v[2:17]
	ds_read_b128 v[40:43], v200 offset:3072
	s_waitcnt vmcnt(0) lgkmcnt(0)
	v_mfma_f32_32x32x16_bf16 v[2:17], v[18:21], v[40:43], v[2:17]
	ds_read_b128 v[40:43], v199 offset:33792
	s_nop 10
	v_mul_f32_e32 v0, 0.5, v2
	v_mul_f32_e32 v39, 0.5, v3
	v_mul_f32_e32 v44, 0.5, v4
	v_mul_f32_e32 v45, 0.5, v5
	ds_read_b128 v[2:5], v199 offset:32768
	v_mul_f32_e32 v46, 0.5, v6
	v_mul_f32_e32 v47, 0.5, v7
	v_mul_f32_e32 v48, 0.5, v8
	v_mul_f32_e32 v49, 0.5, v9
	v_mul_f32_e32 v50, 0.5, v10
	v_mul_f32_e32 v51, 0.5, v11
	v_mul_f32_e32 v52, 0.5, v12
	v_mul_f32_e32 v53, 0.5, v13
	v_mul_f32_e32 v54, 0.5, v14
	v_mul_f32_e32 v55, 0.5, v15
	v_mul_f32_e32 v56, 0.5, v16
	v_mul_f32_e32 v57, 0.5, v17
	s_waitcnt lgkmcnt(0)
	v_mfma_f32_32x32x16_bf16 v[2:17], v[30:33], v[2:5], 0
	v_mfma_f32_32x32x16_bf16 v[2:17], v[26:29], v[40:43], v[2:17]
	ds_read_b128 v[40:43], v199 offset:34816
	s_waitcnt lgkmcnt(0)
	v_mfma_f32_32x32x16_bf16 v[2:17], v[22:25], v[40:43], v[2:17]
	ds_read_b128 v[40:43], v199 offset:35840
	s_waitcnt lgkmcnt(0)
	v_mfma_f32_32x32x16_bf16 v[2:17], v[18:21], v[40:43], v[2:17]
	ds_read_b128 v[40:43], v199 offset:37888
	s_nop 10
	v_fma_f32 v0, v190, |v2|, v0
	v_fma_f32 v39, v190, |v3|, v39
	v_fma_f32 v44, v190, |v4|, v44
	v_fma_f32 v45, v190, |v5|, v45
	ds_read_b128 v[2:5], v199 offset:36864
	v_fma_f32 v46, v190, |v6|, v46
	v_fma_f32 v47, v190, |v7|, v47
	v_fma_f32 v48, v190, |v8|, v48
	v_fma_f32 v49, v190, |v9|, v49
	v_fma_f32 v50, v190, |v10|, v50
	v_fma_f32 v51, v190, |v11|, v51
	v_fma_f32 v52, v190, |v12|, v52
	v_fma_f32 v53, v190, |v13|, v53
	v_fma_f32 v54, v190, |v14|, v54
	v_fma_f32 v55, v190, |v15|, v55
	v_fma_f32 v56, v190, |v16|, v56
	v_fma_f32 v57, v190, |v17|, v57
	s_waitcnt lgkmcnt(0)
	v_mfma_f32_32x32x16_bf16 v[2:17], v[30:33], v[2:5], 0
	v_mfma_f32_32x32x16_bf16 v[2:17], v[26:29], v[40:43], v[2:17]
	ds_read_b128 v[40:43], v199 offset:38912
	s_waitcnt lgkmcnt(0)
	v_mfma_f32_32x32x16_bf16 v[2:17], v[22:25], v[40:43], v[2:17]
	ds_read_b128 v[40:43], v199 offset:39936
	s_waitcnt lgkmcnt(0)
	v_mfma_f32_32x32x16_bf16 v[2:17], v[18:21], v[40:43], v[2:17]
	ds_read_b128 v[40:43], v199 offset:41984
	s_nop 10
	v_fma_f32 v0, v191, |v2|, v0
	v_fma_f32 v39, v191, |v3|, v39
	v_fma_f32 v44, v191, |v4|, v44
	v_fma_f32 v45, v191, |v5|, v45
	ds_read_b128 v[2:5], v199 offset:40960
	v_fma_f32 v46, v191, |v6|, v46
	v_fma_f32 v47, v191, |v7|, v47
	v_fma_f32 v48, v191, |v8|, v48
	v_fma_f32 v49, v191, |v9|, v49
	v_fma_f32 v50, v191, |v10|, v50
	v_fma_f32 v51, v191, |v11|, v51
	v_fma_f32 v52, v191, |v12|, v52
	v_fma_f32 v53, v191, |v13|, v53
	v_fma_f32 v54, v191, |v14|, v54
	v_fma_f32 v55, v191, |v15|, v55
	v_fma_f32 v56, v191, |v16|, v56
	v_fma_f32 v57, v191, |v17|, v57
	s_waitcnt lgkmcnt(0)
	v_mfma_f32_32x32x16_bf16 v[2:17], v[30:33], v[2:5], 0
	v_mfma_f32_32x32x16_bf16 v[2:17], v[26:29], v[40:43], v[2:17]
	ds_read_b128 v[40:43], v199 offset:43008
	s_waitcnt lgkmcnt(0)
	v_mfma_f32_32x32x16_bf16 v[2:17], v[22:25], v[40:43], v[2:17]
	ds_read_b128 v[40:43], v199 offset:44032
	s_waitcnt lgkmcnt(0)
; #define MFMA32(a, b, c) __builtin_amdgcn_mfma_f32_32x32x16_bf16((a), (b), (c), 0, 0, 0)
;     ...
;     for (int hd = 0; hd < 8; ++hd) {
;       f32x16 acc;
;       for (int i = 0; i < 16; ++i) acc[i] = 0.f;
;       #pragma unroll
;       for (int s = 0; s < 4; ++s) acc = MFMA32(a[s], fq[(hd * 4 + s) * 64 + lane], acc);
;       for (int i = 0; i < 16; ++i) sc[i] = fmaf(wv[hd], __builtin_fabsf(acc[i]), sc[i]);
;     }
	v_mfma_f32_32x32x16_bf16 v[2:17], v[18:21], v[40:43], v[2:17]
	ds_read_b128 v[40:43], v199 offset:46080
	s_nop 10
	v_fma_f32 v0, v192, |v2|, v0
	v_fma_f32 v39, v192, |v3|, v39
	v_fma_f32 v44, v192, |v4|, v44
	v_fma_f32 v45, v192, |v5|, v45
	ds_read_b128 v[2:5], v199 offset:45056
	v_fma_f32 v46, v192, |v6|, v46
	v_fma_f32 v47, v192, |v7|, v47
	v_fma_f32 v48, v192, |v8|, v48
	v_fma_f32 v49, v192, |v9|, v49
	v_fma_f32 v50, v192, |v10|, v50
	v_fma_f32 v51, v192, |v11|, v51
	v_fma_f32 v52, v192, |v12|, v52
	v_fma_f32 v53, v192, |v13|, v53
	v_fma_f32 v54, v192, |v14|, v54
	v_fma_f32 v55, v192, |v15|, v55
	v_fma_f32 v56, v192, |v16|, v56
	v_fma_f32 v57, v192, |v17|, v57
	s_waitcnt lgkmcnt(0)
	v_mfma_f32_32x32x16_bf16 v[2:17], v[30:33], v[2:5], 0
	v_mfma_f32_32x32x16_bf16 v[2:17], v[26:29], v[40:43], v[2:17]
	ds_read_b128 v[40:43], v199 offset:47104
	s_waitcnt lgkmcnt(0)
	v_mfma_f32_32x32x16_bf16 v[2:17], v[22:25], v[40:43], v[2:17]
	ds_read_b128 v[40:43], v199 offset:48128
	s_waitcnt lgkmcnt(0)
	v_mfma_f32_32x32x16_bf16 v[2:17], v[18:21], v[40:43], v[2:17]
	ds_read_b128 v[40:43], v199 offset:50176
	s_nop 10
	v_fma_f32 v0, v193, |v2|, v0
	v_fma_f32 v39, v193, |v3|, v39
	v_fma_f32 v44, v193, |v4|, v44
	v_fma_f32 v45, v193, |v5|, v45
	ds_read_b128 v[2:5], v199 offset:49152
	v_fma_f32 v46, v193, |v6|, v46
	v_fma_f32 v47, v193, |v7|, v47
	v_fma_f32 v48, v193, |v8|, v48
	v_fma_f32 v49, v193, |v9|, v49
	v_fma_f32 v50, v193, |v10|, v50
	v_fma_f32 v51, v193, |v11|, v51
	v_fma_f32 v52, v193, |v12|, v52
	v_fma_f32 v53, v193, |v13|, v53
	v_fma_f32 v54, v193, |v14|, v54
	v_fma_f32 v55, v193, |v15|, v55
	v_fma_f32 v56, v193, |v16|, v56
	v_fma_f32 v57, v193, |v17|, v57
	s_waitcnt lgkmcnt(0)
	v_mfma_f32_32x32x16_bf16 v[2:17], v[30:33], v[2:5], 0
	v_mfma_f32_32x32x16_bf16 v[2:17], v[26:29], v[40:43], v[2:17]
	ds_read_b128 v[40:43], v199 offset:51200
	s_waitcnt lgkmcnt(0)
	v_mfma_f32_32x32x16_bf16 v[2:17], v[22:25], v[40:43], v[2:17]
	ds_read_b128 v[40:43], v199 offset:52224
	s_waitcnt lgkmcnt(0)
	v_mfma_f32_32x32x16_bf16 v[2:17], v[18:21], v[40:43], v[2:17]
	ds_read_b128 v[40:43], v199 offset:54272
	s_nop 10
	v_fma_f32 v0, v194, |v2|, v0
	v_fma_f32 v39, v194, |v3|, v39
	v_fma_f32 v44, v194, |v4|, v44
	v_fma_f32 v45, v194, |v5|, v45
	ds_read_b128 v[2:5], v199 offset:53248
	v_fma_f32 v46, v194, |v6|, v46
	v_fma_f32 v47, v194, |v7|, v47
	v_fma_f32 v48, v194, |v8|, v48
	v_fma_f32 v49, v194, |v9|, v49
	v_fma_f32 v50, v194, |v10|, v50
	v_fma_f32 v51, v194, |v11|, v51
	v_fma_f32 v52, v194, |v12|, v52
	v_fma_f32 v53, v194, |v13|, v53
	v_fma_f32 v54, v194, |v14|, v54
	v_fma_f32 v55, v194, |v15|, v55
	v_fma_f32 v56, v194, |v16|, v56
	v_fma_f32 v57, v194, |v17|, v57
	s_waitcnt lgkmcnt(0)
	v_mfma_f32_32x32x16_bf16 v[2:17], v[30:33], v[2:5], 0
	v_mfma_f32_32x32x16_bf16 v[2:17], v[26:29], v[40:43], v[2:17]
	ds_read_b128 v[40:43], v199 offset:55296
	s_waitcnt lgkmcnt(0)
	v_mfma_f32_32x32x16_bf16 v[2:17], v[22:25], v[40:43], v[2:17]
	ds_read_b128 v[40:43], v199 offset:56320
	s_waitcnt lgkmcnt(0)
	v_mfma_f32_32x32x16_bf16 v[2:17], v[18:21], v[40:43], v[2:17]
	ds_read_b128 v[40:43], v199 offset:58368
	s_nop 10
	v_fma_f32 v0, v195, |v2|, v0
	v_fma_f32 v39, v195, |v3|, v39
	v_fma_f32 v44, v195, |v4|, v44
	v_fma_f32 v45, v195, |v5|, v45
	ds_read_b128 v[2:5], v199 offset:57344
	v_fma_f32 v46, v195, |v6|, v46
	v_fma_f32 v47, v195, |v7|, v47
	v_fma_f32 v48, v195, |v8|, v48
	v_fma_f32 v49, v195, |v9|, v49
	v_fma_f32 v50, v195, |v10|, v50
	v_fma_f32 v51, v195, |v11|, v51
	v_fma_f32 v52, v195, |v12|, v52
	v_fma_f32 v53, v195, |v13|, v53
	v_fma_f32 v54, v195, |v14|, v54
	v_fma_f32 v55, v195, |v15|, v55
	v_fma_f32 v56, v195, |v16|, v56
	v_fma_f32 v57, v195, |v17|, v57
	s_waitcnt lgkmcnt(0)
	v_mfma_f32_32x32x16_bf16 v[2:17], v[30:33], v[2:5], 0
	v_mfma_f32_32x32x16_bf16 v[2:17], v[26:29], v[40:43], v[2:17]
	ds_read_b128 v[40:43], v199 offset:59392
	s_waitcnt lgkmcnt(0)
	v_mfma_f32_32x32x16_bf16 v[2:17], v[22:25], v[40:43], v[2:17]
	ds_read_b128 v[40:43], v199 offset:60416
	s_waitcnt lgkmcnt(0)
	v_mfma_f32_32x32x16_bf16 v[2:17], v[18:21], v[40:43], v[2:17]
	s_nop 11
	v_fma_f32 v0, v196, |v2|, v0
	v_fma_f32 v39, v196, |v3|, v39
	v_fma_f32 v40, v196, |v4|, v44
	v_fma_f32 v41, v196, |v5|, v45
	ds_read_b128 v[2:5], v199 offset:61440
	v_fma_f32 v42, v196, |v6|, v46
	v_fma_f32 v43, v196, |v7|, v47
	v_fma_f32 v44, v196, |v8|, v48
	v_fma_f32 v45, v196, |v9|, v49
	v_fma_f32 v46, v196, |v10|, v50
	v_fma_f32 v47, v196, |v11|, v51
	v_fma_f32 v48, v196, |v12|, v52
	v_fma_f32 v49, v196, |v13|, v53
	v_fma_f32 v50, v196, |v14|, v54
	v_fma_f32 v51, v196, |v15|, v55
	v_fma_f32 v52, v196, |v16|, v56
	v_fma_f32 v53, v196, |v17|, v57
	s_waitcnt lgkmcnt(0)
	v_mfma_f32_32x32x16_bf16 v[2:17], v[30:33], v[2:5], 0
	ds_read_b128 v[30:33], v199 offset:62464
	s_waitcnt lgkmcnt(0)
	v_mfma_f32_32x32x16_bf16 v[2:17], v[26:29], v[30:33], v[2:17]
	ds_read_b128 v[26:29], v199 offset:63488
	s_waitcnt lgkmcnt(0)
	v_mfma_f32_32x32x16_bf16 v[2:17], v[22:25], v[26:29], v[2:17]
	ds_read_b128 v[22:25], v199 offset:64512
	s_waitcnt lgkmcnt(0)
; DI int crow(int reg, int h) { return (reg & 3) + 8 * (reg >> 2) + 4 * h; }
; #define MFMA32(a, b, c) __builtin_amdgcn_mfma_f32_32x32x16_bf16((a), (b), (c), 0, 0, 0)
;     ...
;       for (int s = 0; s < 4; ++s) acc = MFMA32(a[s], fq[(hd * 4 + s) * 64 + lane], acc);
;       for (int i = 0; i < 16; ++i) sc[i] = fmaf(wv[hd], __builtin_fabsf(acc[i]), sc[i]);
;     }
;     f(sc, kt);
; DI void dsa_item(const Params& p, int b, int blk) {
;     ...
;       score_pass(Ikb, wv, kt_s + 1, kt_s, lane, [&](const f32x16& sc, int kt) {
;         float s1 = 0.f, s2 = 0.f, c = 0.f;
;         for (int i = 0; i < 16; ++i) { int key = kt * 32 + crow(i, hh); if (key <= qpos) { s1 += sc[i]; s2 += sc[i] * sc[i]; c += 1.f; } }
;         atomicAdd(&ssum[r], s1); atomicAdd(&ssq[r], s2); atomicAdd(&scnt[r], c);
;       });
;     }
;     __syncthreads();
;     float b_lo, b_sc;
;     {
;       const float n = fmaxf(scnt[r], 1.f), mu = ssum[r] / n, var = fmaxf(ssq[r] / n - mu * mu, 0.f), sd = sqrtf(var);
;       b_lo = mu - 3.5f * sd; b_sc = sd > 1e-20f ? 32.f / sd : 0.f;
;     }
;     auto binof = [&](float s) -> unsigned { return (unsigned)(int)fminf(fmaxf(__fmul_rn(__fsub_rn(s, b_lo), b_sc), 0.f), 255.f); };
;     score_pass(Ikb, wv, nt, w, lane, [&](const f32x16& sc, int kt) {
	v_mfma_f32_32x32x16_bf16 v[2:17], v[18:21], v[22:25], v[2:17]
	s_nop 11
	v_fma_f32 v0, v197, |v2|, v0
	v_fma_f32 v2, v197, |v3|, v39
	v_fma_f32 v3, v197, |v4|, v40
	v_fma_f32 v4, v197, |v5|, v41
	v_fma_f32 v5, v197, |v6|, v42
	v_fma_f32 v6, v197, |v7|, v43
	v_fma_f32 v7, v197, |v8|, v44
	v_fma_f32 v8, v197, |v9|, v45
	v_fma_f32 v9, v197, |v10|, v46
	v_fma_f32 v10, v197, |v11|, v47
	v_fma_f32 v11, v197, |v12|, v48
	v_fma_f32 v12, v197, |v13|, v49
	v_fma_f32 v13, v197, |v14|, v50
	v_fma_f32 v14, v197, |v15|, v51
	v_fma_f32 v15, v197, |v16|, v52
	v_fma_f32 v16, v197, |v17|, v53
	v_or_b32_e32 v17, v38, v201
	v_cmp_gt_i32_e32 vcc, v17, v198
	v_add_f32_e32 v18, 0, v0
	v_mul_f32_e32 v0, v0, v0
	v_cndmask_b32_e64 v0, v0, 0, vcc
	v_cndmask_b32_e64 v19, 1.0, 0, vcc
	v_cndmask_b32_e64 v18, v18, 0, vcc
	v_cmp_lt_i32_e32 vcc, v17, v198
	v_add_f32_e32 v20, v2, v18
	v_fma_f32 v2, v2, v2, v0
	v_add_f32_e32 v21, 1.0, v19
	v_cndmask_b32_e32 v0, v0, v2, vcc
	v_cndmask_b32_e32 v2, v19, v21, vcc
	v_cndmask_b32_e32 v18, v18, v20, vcc
	v_or_b32_e32 v19, 2, v17
	v_cmp_gt_i32_e32 vcc, v19, v198
	v_add_f32_e32 v19, v3, v18
	v_fma_f32 v3, v3, v3, v0
	v_add_f32_e32 v20, 1.0, v2
	v_cndmask_b32_e32 v0, v3, v0, vcc
	v_cndmask_b32_e32 v2, v20, v2, vcc
	v_cndmask_b32_e32 v3, v19, v18, vcc
	v_or_b32_e32 v18, 3, v17
	v_cmp_gt_i32_e32 vcc, v18, v198
	v_add_f32_e32 v18, v4, v3
	v_fma_f32 v4, v4, v4, v0
	v_add_f32_e32 v19, 1.0, v2
	v_cndmask_b32_e32 v0, v4, v0, vcc
	v_cndmask_b32_e32 v2, v19, v2, vcc
	v_cndmask_b32_e32 v3, v18, v3, vcc
	v_or_b32_e32 v4, 8, v17
	v_cmp_gt_i32_e32 vcc, v4, v198
	v_add_f32_e32 v4, v5, v3
	v_fma_f32 v5, v5, v5, v0
	v_add_f32_e32 v18, 1.0, v2
	v_cndmask_b32_e32 v0, v5, v0, vcc
	v_cndmask_b32_e32 v2, v18, v2, vcc
	v_cndmask_b32_e32 v3, v4, v3, vcc
	v_or_b32_e32 v4, 9, v17
	v_cmp_gt_i32_e32 vcc, v4, v198
	v_add_f32_e32 v4, v6, v3
	v_fma_f32 v5, v6, v6, v0
	v_add_f32_e32 v6, 1.0, v2
	v_cndmask_b32_e32 v2, v6, v2, vcc
	v_cndmask_b32_e32 v3, v4, v3, vcc
	v_or_b32_e32 v4, 10, v17
	v_cndmask_b32_e32 v0, v5, v0, vcc
	v_cmp_gt_i32_e32 vcc, v4, v198
	v_add_f32_e32 v4, v7, v3
	v_add_f32_e32 v6, 1.0, v2
	v_fma_f32 v5, v7, v7, v0
	v_cndmask_b32_e32 v2, v6, v2, vcc
	v_cndmask_b32_e32 v3, v4, v3, vcc
	v_or_b32_e32 v4, 11, v17
	v_cndmask_b32_e32 v0, v5, v0, vcc
	v_cmp_gt_i32_e32 vcc, v4, v198
	v_add_f32_e32 v4, v8, v3
	v_add_f32_e32 v6, 1.0, v2
	v_fma_f32 v5, v8, v8, v0
	v_cndmask_b32_e32 v2, v6, v2, vcc
	v_cndmask_b32_e32 v3, v4, v3, vcc
	v_or_b32_e32 v4, 16, v17
	v_cndmask_b32_e32 v0, v5, v0, vcc
	v_cmp_gt_i32_e32 vcc, v4, v198
	v_add_f32_e32 v4, v9, v3
	v_add_f32_e32 v6, 1.0, v2
	v_fma_f32 v5, v9, v9, v0
	v_cndmask_b32_e32 v2, v6, v2, vcc
	v_cndmask_b32_e32 v3, v4, v3, vcc
	v_or_b32_e32 v4, 17, v17
	v_cndmask_b32_e32 v0, v5, v0, vcc
	v_cmp_gt_i32_e32 vcc, v4, v198
	v_add_f32_e32 v4, v10, v3
	v_add_f32_e32 v6, 1.0, v2
	v_fma_f32 v5, v10, v10, v0
	v_cndmask_b32_e32 v2, v6, v2, vcc
	v_cndmask_b32_e32 v3, v4, v3, vcc
	v_or_b32_e32 v4, 18, v17
	v_cndmask_b32_e32 v0, v5, v0, vcc
	v_cmp_gt_i32_e32 vcc, v4, v198
	v_add_f32_e32 v4, v11, v3
	v_add_f32_e32 v6, 1.0, v2
	v_fma_f32 v5, v11, v11, v0
	v_cndmask_b32_e32 v2, v6, v2, vcc
	v_cndmask_b32_e32 v3, v4, v3, vcc
	v_or_b32_e32 v4, 19, v17
	v_cndmask_b32_e32 v0, v5, v0, vcc
	v_cmp_gt_i32_e32 vcc, v4, v198
	v_add_f32_e32 v4, v12, v3
	v_add_f32_e32 v6, 1.0, v2
	v_fma_f32 v5, v12, v12, v0
	v_cndmask_b32_e32 v2, v6, v2, vcc
	v_cndmask_b32_e32 v3, v4, v3, vcc
	v_or_b32_e32 v4, 24, v17
	v_cndmask_b32_e32 v0, v5, v0, vcc
	v_cmp_gt_i32_e32 vcc, v4, v198
	v_add_f32_e32 v4, v13, v3
	v_add_f32_e32 v6, 1.0, v2
	v_fma_f32 v5, v13, v13, v0
	v_cndmask_b32_e32 v2, v6, v2, vcc
	v_cndmask_b32_e32 v3, v4, v3, vcc
	v_or_b32_e32 v4, 25, v17
	v_cndmask_b32_e32 v0, v5, v0, vcc
	v_cmp_gt_i32_e32 vcc, v4, v198
	v_add_f32_e32 v4, v14, v3
	v_add_f32_e32 v6, 1.0, v2
	v_fma_f32 v5, v14, v14, v0
	v_cndmask_b32_e32 v2, v6, v2, vcc
	v_cndmask_b32_e32 v3, v4, v3, vcc
	v_or_b32_e32 v4, 26, v17
	v_cndmask_b32_e32 v0, v5, v0, vcc
	v_cmp_gt_i32_e32 vcc, v4, v198
	v_add_f32_e32 v4, v15, v3
	v_add_f32_e32 v6, 1.0, v2
	v_fma_f32 v5, v15, v15, v0
	v_cndmask_b32_e32 v2, v6, v2, vcc
	v_cndmask_b32_e32 v3, v4, v3, vcc
	v_or_b32_e32 v4, 27, v17
	v_cndmask_b32_e32 v0, v5, v0, vcc
	v_cmp_gt_i32_e32 vcc, v4, v198
	v_add_f32_e32 v4, v16, v3
	v_add_f32_e32 v6, 1.0, v2
	v_fma_f32 v5, v16, v16, v0
	v_cndmask_b32_e32 v2, v6, v2, vcc
	v_cndmask_b32_e32 v3, v4, v3, vcc
	v_cndmask_b32_e32 v0, v5, v0, vcc
	ds_add_f32 v37, v3
	ds_add_f32 v35, v0
	ds_add_f32 v36, v2
	s_waitcnt lgkmcnt(0)
	s_barrier
	ds_read_b32 v4, v36
	ds_read_b32 v3, v37
	ds_read_b32 v2, v35
	v_lshlrev_b32_e32 v0, 1, v34
	s_and_saveexec_b64 s[0:1], s[8:9]
	s_cbranch_execz .LBB0_952
	v_lshl_or_b32 v6, v188, 5, v202
	v_ashrrev_i32_e32 v7, 31, v6
	v_lshlrev_b64 v[6:7], 7, v[6:7]
	v_lshl_add_u64 v[6:7], s[4:5], 0, v[6:7]
	v_lshl_add_u64 v[6:7], v[6:7], 0, v[0:1]
	global_load_dwordx4 v[130:133], v[6:7], off
	global_load_dwordx4 v[162:165], v[6:7], off offset:32
	global_load_dwordx4 v[166:169], v[6:7], off offset:64
	global_load_dwordx4 v[170:173], v[6:7], off offset:96
